# resid GEMM tile order: XCD-local 8x8 (row x col) patches per round for L2 reuse
# speedup vs baseline: 1.0381x; 1.0189x over previous
; __device__ __forceinline__ int tidx() { int t = threadIdx.x; asm volatile("" : "+v"(t)); return t; }
; template <int NT>
; __device__ __forceinline__ void gemm_tile(f32x4 (&acc)[4][NT], const bf16_t* A, int lda, const bf16_t* B, int ldb, int K, bf16_t* sm) {
;     const int tid_ = tidx();
;     bf16_t* sA = sm; bf16_t* sB = sm + 128 * LDT;
;     const int tid = tid_, lane = tid & 63, wid = tid >> 6, wr = wid >> 1, wc = wid & 1;
;     const int fr = lane & 15, fq = lane >> 4;
;     const int lrow = tid >> 3, lkc = tid & 7;
;     const bf16_t* ga = A + (size_t)lrow * lda + lkc * 8;
;     const bf16_t* gb = B + (size_t)lrow * ldb + lkc * 8;
;     int sbrow[NT];
; #pragma unroll
;     for (int i = 0; i < NT; ++i) { const int g = lrow + 32 * i, W_ = 16 * NT, rem = g % W_; sbrow[i] = (g / W_) * W_ + (rem % NT) * 16 + rem / NT; }
; __device__ __forceinline__ void phase_gemm_resid(const bf16_t* A, int lda, int K, const bf16_t* W, const float* X, float* Y, float scale, bf16_t* sm) {
;     const int G = gridDim.x, NTILES = 136 * 8;
;     const int nfull = (NTILES / G) * G;
;     for (int t = blockIdx.x; t < nfull; t += G) resid_tile<4>(t >> 3, (t & 7) * 128, A, lda, K, W, X, Y, scale, sm);
.LBB0_35:
	v_mov_b32_e32 v118, v192
	v_mov_b32_e32 v36, v192
	s_and_b32 s18, s39, 7
	s_lshl_b32 s18, s18, 3
	s_bfe_u32 s19, s39, 0x30006
	s_or_b32 s18, s18, s19
	s_ashr_i32 s19, s39, 9
	s_lshl_b32 s19, s19, 6
	s_or_b32 s18, s18, s19
	v_ashrrev_i32_e32 v0, 31, v36
	v_ashrrev_i32_e32 v34, 3, v36
	v_lshrrev_b32_e32 v0, 26, v0
	v_add_u32_e32 v0, v34, v0
	v_lshrrev_b32_e32 v1, 6, v0
	v_mul_i32_i24_e32 v1, 64, v1
	v_sub_u32_e32 v1, v34, v1
	v_lshrrev_b16_sdwa v2, v196, sext(v1) dst_sel:DWORD dst_unused:UNUSED_PAD src0_sel:DWORD src1_sel:BYTE_0
	v_and_b32_e32 v2, 3, v2
	v_add_u16_e32 v2, v1, v2
	v_ashrrev_i16_sdwa v3, v197, sext(v2) dst_sel:DWORD dst_unused:UNUSED_PAD src0_sel:DWORD src1_sel:BYTE_0
	v_and_b32_e32 v2, 0xfc, v2
	v_sub_u16_e32 v1, v1, v2
	v_and_b32_e32 v0, 0x7ffffc0, v0
	v_lshlrev_b32_sdwa v1, v198, sext(v1) dst_sel:DWORD dst_unused:UNUSED_PAD src0_sel:DWORD src1_sel:BYTE_0
	v_bfe_i32 v2, v3, 0, 16
	v_add3_u32 v37, v0, v2, v1
	v_add_u32_e32 v0, 32, v34
	v_ashrrev_i32_e32 v1, 31, v0
	v_lshrrev_b32_e32 v1, 26, v1
	v_add_u32_e32 v1, v0, v1
	v_lshrrev_b32_e32 v2, 6, v1
	v_mul_i32_i24_e32 v2, 64, v2
	v_sub_u32_e32 v0, v0, v2
	v_lshrrev_b16_sdwa v2, v196, sext(v0) dst_sel:DWORD dst_unused:UNUSED_PAD src0_sel:DWORD src1_sel:BYTE_0
	v_and_b32_e32 v2, 3, v2
	v_add_u16_e32 v2, v0, v2
	v_ashrrev_i16_sdwa v3, v197, sext(v2) dst_sel:DWORD dst_unused:UNUSED_PAD src0_sel:DWORD src1_sel:BYTE_0
	v_and_b32_e32 v2, 0xfc, v2
	v_sub_u16_e32 v0, v0, v2
	v_and_b32_e32 v1, 0x7ffffc0, v1
	v_lshlrev_b32_sdwa v0, v198, sext(v0) dst_sel:DWORD dst_unused:UNUSED_PAD src0_sel:DWORD src1_sel:BYTE_0
	v_bfe_i32 v2, v3, 0, 16
	v_add3_u32 v38, v1, v2, v0
	v_add_u32_e32 v0, 64, v34
	v_ashrrev_i32_e32 v1, 31, v0
	v_lshrrev_b32_e32 v1, 26, v1
	v_add_u32_e32 v1, v0, v1
	v_lshrrev_b32_e32 v2, 6, v1
	v_mul_i32_i24_e32 v2, 64, v2
	v_sub_u32_e32 v0, v0, v2
	v_lshrrev_b16_sdwa v2, v196, sext(v0) dst_sel:DWORD dst_unused:UNUSED_PAD src0_sel:DWORD src1_sel:BYTE_0
	v_and_b32_e32 v2, 3, v2
	v_add_u16_e32 v2, v0, v2
	v_ashrrev_i16_sdwa v3, v197, sext(v2) dst_sel:DWORD dst_unused:UNUSED_PAD src0_sel:DWORD src1_sel:BYTE_0
	v_and_b32_e32 v2, 0xfc, v2
	v_sub_u16_e32 v0, v0, v2
	v_and_b32_e32 v1, 0x7ffffc0, v1
	v_lshlrev_b32_sdwa v0, v198, sext(v0) dst_sel:DWORD dst_unused:UNUSED_PAD src0_sel:DWORD src1_sel:BYTE_0
	v_bfe_i32 v2, v3, 0, 16
	v_add3_u32 v39, v1, v2, v0
	v_add_u32_e32 v0, 0x60, v34
	v_ashrrev_i32_e32 v1, 31, v0
	v_lshrrev_b32_e32 v1, 26, v1
	v_add_u32_e32 v1, v0, v1
	v_lshrrev_b32_e32 v2, 6, v1
	v_mul_i32_i24_e32 v2, 64, v2
	v_sub_u32_e32 v0, v0, v2
	s_ashr_i32 s19, s18, 31
	v_lshrrev_b16_sdwa v2, v196, sext(v0) dst_sel:DWORD dst_unused:UNUSED_PAD src0_sel:DWORD src1_sel:BYTE_0
	s_lshl_b32 s2, s39, 4
	s_lshl_b64 s[76:77], s[18:19], s97
	v_and_b32_e32 v2, 3, v2
	s_and_b32 s2, s2, 0x380
	s_lshl_b64 s[78:79], s[76:77], 1
	v_add_u16_e32 v2, v0, v2
	s_add_u32 s84, s12, s78
	v_ashrrev_i16_sdwa v3, v197, sext(v2) dst_sel:DWORD dst_unused:UNUSED_PAD src0_sel:DWORD src1_sel:BYTE_0
	v_and_b32_e32 v2, 0xfc, v2
	s_addc_u32 s85, s11, s79
	s_lshl_b32 s19, s2, vcc_lo
	v_sub_u16_e32 v0, v0, v2
	s_lshl_b32 s19, s19, 1
	v_and_b32_e32 v1, 0x7ffffc0, v1
	v_lshlrev_b32_sdwa v0, v198, sext(v0) dst_sel:DWORD dst_unused:UNUSED_PAD src0_sel:DWORD src1_sel:BYTE_0
	v_bfe_i32 v2, v3, 0, 16
	v_ashrrev_i32_e32 v35, 31, v34
	s_add_u32 s76, s13, s19
	v_add3_u32 v40, v1, v2, v0
	v_lshlrev_b64 v[0:1], vcc_lo, v[34:35]
	s_addc_u32 s77, s94, 0
	v_lshlrev_b64 v[100:101], 1, v[0:1]
	v_lshlrev_b32_e32 v2, 4, v36
	v_lshl_add_u64 v[0:1], s[76:77], 0, v[100:101]
	v_and_b32_e32 v12, 0x70, v2
	v_lshl_add_u64 v[18:19], s[84:85], 0, v[100:101]
	v_lshl_add_u64 v[4:5], v[0:1], 0, v[12:13]
	s_mov_b32 s75, s87
	s_mov_b32 s83, s87
	v_lshl_add_u64 v[18:19], v[18:19], 0, v[12:13]
	v_lshl_add_u64 v[0:1], v[4:5], 0, s[86:87]
	v_lshl_add_u64 v[6:7], v[4:5], 0, s[74:75]
	v_lshl_add_u64 v[14:15], v[4:5], 0, s[82:83]
	v_lshl_add_u64 v[20:21], v[18:19], 0, s[86:87]
	v_mov_b32_e32 v250, v4
	v_mov_b32_e32 v251, v5
	s_nop 0
	s_nop 0
	s_nop 0
	s_nop 0
	v_mov_b32_e32 v248, v18
	v_mov_b32_e32 v249, v19
	v_lshl_add_u64 v[20:21], v[18:19], 0, s[74:75]
	v_lshl_add_u64 v[26:27], v[18:19], 0, s[82:83]
	s_nop 0
	v_and_b32_e32 v35, 15, v36
	v_lshrrev_b32_e32 v42, 1, v36
	v_and_or_b32 v35, v42, s3, v35
	v_mul_lo_u32 v42, v35, s89
	v_mul_lo_u32 v43, v34, s89
	v_lshl_add_u64 v[34:35], v[12:13], 0, s[78:79]
	v_and_b32_e32 v41, 48, v36
	v_and_b32_e32 v36, 0x4f, v36
	v_lshl_add_u64 v[102:103], s[42:43], 0, v[34:35]
	v_lshl_add_u64 v[104:105], s[44:45], 0, v[34:35]
	v_lshl_add_u64 v[106:107], s[46:47], 0, v[34:35]
	v_lshl_add_u64 v[108:109], s[40:41], 0, v[34:35]
	v_or_b32_e32 v34, s19, v12
	v_mov_b32_e32 v35, v13
	v_mul_u32_u24_e32 v36, 0xa0, v36
	v_mul_lo_u32 v37, v37, s89
	v_mul_lo_u32 v38, v38, s89
	v_mul_lo_u32 v39, v39, s89
	v_mul_lo_u32 v40, v40, s89
	v_lshl_add_u64 v[110:111], s[48:49], 0, v[34:35]
	v_lshl_add_u64 v[112:113], s[50:51], 0, v[34:35]
	v_lshl_add_u64 v[114:115], s[52:53], 0, v[34:35]
	v_lshl_add_u64 v[116:117], s[54:55], 0, v[34:35]
	v_mov_b32_e32 v34, 0
	v_add_u32_e32 v120, v12, v43
	v_add_u32_e32 v121, v12, v37
	v_add_u32_e32 v122, v12, v38
	v_add_u32_e32 v123, v12, v39
	v_add_u32_e32 v124, v12, v40
	v_add_u32_e32 v119, v41, v42
; template <int NT>
; __device__ __forceinline__ void gemm_tile(f32x4 (&acc)[4][NT], const bf16_t* A, int lda, const bf16_t* B, int ldb, int K, bf16_t* sm) {
;     ...
;     const bf16_t* ga = A + (size_t)lrow * lda + lkc * 8;
;     const bf16_t* gb = B + (size_t)lrow * ldb + lkc * 8;
;     int sbrow[NT];
; #pragma unroll
;     for (int i = 0; i < NT; ++i) { const int g = lrow + 32 * i, W_ = 16 * NT, rem = g % W_; sbrow[i] = (g / W_) * W_ + (rem % NT) * 16 + rem / NT; }
;     u32x4 ra0[4], rb0[NT];
; #pragma unroll
;     for (int i = 0; i < 4; ++i) ra0[i] = *(const u32x4*)(ga + (size_t)(32 * i) * lda);
; #pragma unroll
;     for (int i = 0; i < NT; ++i) rb0[i] = *(const u32x4*)(gb + (size_t)(32 * i) * ldb);
;     const int nk = K >> 6;
;     for (int kt = 0; kt < nk; ++kt) {
;         lds_barrier();
; #pragma unroll
;         for (int i = 0; i < 4; ++i) *(u32x4*)(sA + (lrow + 32 * i) * LDT + lkc * 8) = ra0[i];
; #pragma unroll
;         for (int i = 0; i < NT; ++i) *(u32x4*)(sB + sbrow[i] * LDT + lkc * 8) = rb0[i];
;         lds_barrier();
;         if (kt + 1 < nk) {
;             ga += 64; gb += 64;
; #pragma unroll
;             for (int i = 0; i < 4; ++i) ra0[i] = *(const u32x4*)(ga + (size_t)(32 * i) * lda);
; #pragma unroll
;             for (int i = 0; i < NT; ++i) rb0[i] = *(const u32x4*)(gb + (size_t)(32 * i) * ldb);
;         }
	v_add_u32_e32 v12, v41, v36
	s_mov_b32 s19, vcc_hi
	v_mov_b32_e32 v35, v34
	v_mov_b32_e32 v36, v34
	v_mov_b32_e32 v37, v34
	v_mov_b32_e32 v38, v34
	v_mov_b32_e32 v39, v34
	v_mov_b32_e32 v40, v34
	v_mov_b32_e32 v41, v34
	v_mov_b32_e32 v42, v34
	v_mov_b32_e32 v43, v34
	v_mov_b32_e32 v44, v34
	v_mov_b32_e32 v45, v34
	v_mov_b32_e32 v46, v34
	v_mov_b32_e32 v47, v34
	v_mov_b32_e32 v48, v34
	v_mov_b32_e32 v49, v34
	v_mov_b32_e32 v50, v34
	v_mov_b32_e32 v51, v34
	v_mov_b32_e32 v52, v34
	v_mov_b32_e32 v53, v34
	v_mov_b32_e32 v54, v34
	v_mov_b32_e32 v55, v34
	v_mov_b32_e32 v56, v34
	v_mov_b32_e32 v57, v34
	v_mov_b32_e32 v58, v34
	v_mov_b32_e32 v59, v34
	v_mov_b32_e32 v60, v34
	v_mov_b32_e32 v61, v34
	v_mov_b32_e32 v62, v34
	v_mov_b32_e32 v63, v34
	v_mov_b32_e32 v64, v34
	v_mov_b32_e32 v65, v34
	v_mov_b32_e32 v66, v34
	v_mov_b32_e32 v67, v34
	v_mov_b32_e32 v68, v34
	v_mov_b32_e32 v69, v34
	v_mov_b32_e32 v70, v34
	v_mov_b32_e32 v71, v34
	v_mov_b32_e32 v72, v34
	v_mov_b32_e32 v73, v34
	v_mov_b32_e32 v74, v34
	v_mov_b32_e32 v75, v34
	v_mov_b32_e32 v76, v34
	v_mov_b32_e32 v77, v34
	v_mov_b32_e32 v78, v34
	v_mov_b32_e32 v79, v34
	v_mov_b32_e32 v80, v34
	v_mov_b32_e32 v81, v34
	v_mov_b32_e32 v82, v34
	v_mov_b32_e32 v83, v34
	v_mov_b32_e32 v84, v34
	v_mov_b32_e32 v85, v34
	v_mov_b32_e32 v86, v34
	v_mov_b32_e32 v87, v34
	v_mov_b32_e32 v88, v34
	v_mov_b32_e32 v89, v34
	v_mov_b32_e32 v90, v34
	v_mov_b32_e32 v91, v34
	v_mov_b32_e32 v92, v34
	v_mov_b32_e32 v93, v34
	v_mov_b32_e32 v94, v34
	v_mov_b32_e32 v95, v34
	v_mov_b32_e32 v96, v34
	v_mov_b32_e32 v97, v34
	v_writelane_b32 v234, s90, 0
	v_writelane_b32 v234, s91, 1
	v_writelane_b32 v234, s92, 2
	v_writelane_b32 v234, s93, 3
	v_writelane_b32 v234, s94, 4
	v_writelane_b32 v234, s95, 5
	v_bfe_u32 v160, v192, 3, 3
	v_and_b32_e32 v161, 7, v192
	v_xor_b32_e32 v161, v160, v161
	v_lshlrev_b32_e32 v161, 4, v161
	v_lshrrev_b32_e32 v162, 6, v192
	v_lshl_add_u32 v163, v162, 5, v160
	s_lshl_b32 s95, s96, 1
	v_mul_u32_u24_e32 v163, s95, v163
	v_add_u32_e32 v236, v163, v161
	s_lshl_b32 s95, s96, 4
	s_sub_u32 s95, s95, 0x400
	v_add_u32_e32 v237, s95, v236
	v_add_u32_e32 v238, s95, v237
	v_add_u32_e32 v239, s95, v238
	v_lshrrev_b32_e32 v163, 7, v192
	v_bfe_u32 v162, v192, 6, 1
	v_lshlrev_b32_e32 v163, 6, v163
	v_lshl_add_u32 v163, v160, 2, v163
	v_lshl_add_u32 v163, v162, 1, v163
	s_lshl_b32 s95, s96, 1
	v_mul_u32_u24_e32 v163, s95, v163
	v_add_u32_e32 v240, v163, v161
	s_mul_i32 s95, s96, 64
	s_sub_u32 s95, s95, 0x400
	v_add_u32_e32 v241, s95, v240
	s_mul_i32 s95, s96, 62
	s_add_u32 s95, s95, 0x400
	v_subrev_u32_e32 v242, s95, v241
	s_mul_i32 s95, s96, 64
	s_sub_u32 s95, s95, 0x400
	v_add_u32_e32 v243, s95, v242
	v_and_b32_e32 v160, 15, v192
	v_bfe_u32 v161, v192, 4, 2
	v_and_b32_e32 v162, 7, v160
	v_xor_b32_e32 v161, v161, v162
	v_lshlrev_b32_e32 v161, 4, v161
	v_lshl_add_u32 v161, v160, 7, v161
	v_lshrrev_b32_e32 v162, 7, v192
	v_lshl_add_u32 v244, v162, 13, v161
	v_bfe_u32 v162, v192, 6, 1
	v_lshl_add_u32 v246, v162, 13, v161
	v_add_u32_e32 v246, 0x4000, v246
	v_xor_b32_e32 v245, 64, v244
	v_xor_b32_e32 v247, 64, v246
	v_lshrrev_b32_e32 v160, 6, v192
	s_nop 0
	v_readfirstlane_b32 s94, v160
	v_readfirstlane_b32 s90, v248
	v_readfirstlane_b32 s91, v249
	v_readfirstlane_b32 s92, v250
	v_readfirstlane_b32 s93, v251
	s_lshl_b32 s95, s96, 4
	s_mul_i32 s95, s94, s95
	s_sub_u32 s90, s90, s95
	s_subb_u32 s91, s91, 0
	s_lshl_b32 s95, s96, 4
	s_mul_i32 s95, s94, s95
	s_sub_u32 s92, s92, s95
	s_subb_u32 s93, s93, 0
	s_lshl_b32 s94, s94, 10
	s_waitcnt lgkmcnt(0)
	s_barrier
	s_lshl_b32 s95, s94, 2
	s_add_u32 m0, s95, 0x0
	s_nop 0
	global_load_lds_dwordx4 v236, s[90:91]
	global_load_lds_dwordx4 v237, s[90:91] offset:1024
	global_load_lds_dwordx4 v238, s[90:91] offset:2048
	global_load_lds_dwordx4 v239, s[90:91] offset:3072
	s_mul_i32 s95, s94, 4
	s_add_u32 m0, s95, 0x4000
	s_nop 0
	global_load_lds_dwordx4 v240, s[92:93]
	global_load_lds_dwordx4 v241, s[92:93] offset:1024
	global_load_lds_dwordx4 v242, s[92:93] offset:2048
	global_load_lds_dwordx4 v243, s[92:93] offset:3072
	s_add_u32 s90, s90, 0x80
	s_addc_u32 s91, s91, 0
	s_add_u32 s92, s92, 0x80
	s_addc_u32 s93, s93, 0
	s_waitcnt vmcnt(0)
	s_barrier
	s_lshl_b32 s95, s94, 2
	s_add_u32 m0, s95, 0x8000
	s_nop 0
	global_load_lds_dwordx4 v236, s[90:91]
	global_load_lds_dwordx4 v237, s[90:91] offset:1024
	global_load_lds_dwordx4 v238, s[90:91] offset:2048
	global_load_lds_dwordx4 v239, s[90:91] offset:3072
	s_mul_i32 s95, s94, 4
	s_add_u32 m0, s95, 0xc000
	s_nop 0
	global_load_lds_dwordx4 v240, s[92:93]
	global_load_lds_dwordx4 v241, s[92:93] offset:1024
	global_load_lds_dwordx4 v242, s[92:93] offset:2048
	global_load_lds_dwordx4 v243, s[92:93] offset:3072
	s_add_u32 s90, s90, 0x80
	s_addc_u32 s91, s91, 0
	s_add_u32 s92, s92, 0x80
	s_addc_u32 s93, s93, 0
	ds_read_b128 v[126:129], v244 offset:0
	ds_read_b128 v[130:133], v244 offset:2048
	ds_read_b128 v[134:137], v244 offset:4096
	ds_read_b128 v[138:141], v244 offset:6144
	ds_read_b128 v[142:145], v246 offset:0
	ds_read_b128 v[146:149], v246 offset:2048
	ds_read_b128 v[152:155], v246 offset:4096
	ds_read_b128 v[156:159], v246 offset:6144
	s_lshr_b32 s95, s96, 7
	s_add_i32 s95, s95, -2
	s_cmp_eq_u32 s95, 0
	s_cbranch_scc1 .Lgemm_x36
